# diff-attention online softmax as well: row reference as QK MFMA C operand, subtractions only when the reference moves
# speedup vs baseline: 1.0262x; 1.0053x over previous
; template <int MODE>
; __device__ __forceinline__ void attn_unit(LAS char* lds, const AttnPtrs& A, int b, int qb) {
;     ...
;     const int tid = opaque_tid(), lane = tid & 63, r32 = lane & 31, hi = lane >> 5, wid = __builtin_amdgcn_readfirstlane(tid >> 6);
;     const int strm = (MODE == 2) ? (wid & 1) : 0;
;     const size_t rowbase = (size_t)b * SEQ; const int q0 = (MODE == 2) ? qb * 128 + (wid >> 1) * 32 : qb * 256 + wid * 32; const int cw = q0 >> 6, NT = (MODE == 2) ? 2 * qb + 2 : 4 * qb + 4;
;     const size_t qrow = rowbase + q0 + r32;
;     const bf16_t* ksrc[2]; const bf16_t* vsrc[2];
; #pragma unroll
;     for (int i = 0; i < 2; ++i) { const unsigned row = 4u * (2 * wid + i) + (lane >> 4), ch = (lane & 15) ^ (((row & 3) << 2) | ((row >> 2) & 3));
;         ksrc[i] = A.K + (rowbase + row) * A.ldk + ch * 8; vsrc[i] = A.V + (rowbase + row) * A.ldv + ch * 8; }
;     const bf16_t* k64src = nullptr;
;     if constexpr (MODE == 0) { const unsigned row = 8u * wid + (lane >> 3), ch = (lane & 7) ^ ((row >> 1) & 7); k64src = A.K64 + (rowbase + row) * 64 + ch * 8; }
;     const unsigned fK = ((r32 & 3) << 2) | ((r32 >> 2) & 3);
;     const unsigned g64 = (r32 >> 1) & 7;
;     const int q4 = (lane & 15) >> 2, p4 = lane & 3, blk = (lane >> 4) & 1;
;     unsigned vrow[2], vlow[2];
; #pragma unroll
;     for (int t = 0; t < 2; ++t) { vrow[t] = 4 * hi + 8 * t + q4; vlow[t] = (unsigned)((2 * blk + (p4 >> 1)) ^ ((hi + 2 * t) & 3)); }
;     ...
;     STAGE(0, 0); STAGE(1, 1);
;     bf16x8 qf[NQ];
; #pragma unroll
;     for (int s = 0; s < NQ; ++s) qf[s] = *(const bf16x8*)(A.Q + qrow * A.ldq + 64 * strm + 16 * s + 8 * hi);
;     ...
;                 const int qb = 31 - it / 20, bh = it % 20, b = bh / 5, h = bh % 5;
;                 att::AttnPtrs A{QKC + 2 * h * 64, 1280, QKC + 640 + 2 * h * 64, 1280, nullptr, VBC + 640 + h * 128, 1280, GATE + 1408 + h * 128, GATE + 1408 + h * 128, nullptr, lam, 1.0f - lam_init, ap->subln_g + L * 128};
.LBB0_623:
	s_mul_hi_i32 s3, s2, 0x99999999
	s_lshr_b32 s4, s3, 31
	s_ashr_i32 s3, s3, 3
	s_add_i32 s3, s3, s4
	s_mul_hi_i32 s4, s2, 0x66666667
	s_lshr_b32 s5, s4, 31
	s_lshr_b32 s4, s4, 3
	s_add_i32 s4, s4, s5
	s_mul_i32 s4, s4, 20
	s_sub_i32 s4, s2, s4
	s_bfe_i32 s2, s4, 0x80000
	s_mulk_i32 s2, 0x67
	s_sext_i32_i16 s5, s2
	s_ashr_i32 s5, s5, 9
	s_bfe_u32 s2, s2, 0x1000f
	s_add_i32 s2, s5, s2
	s_mul_i32 s5, s2, 5
	s_sub_i32 s4, s4, s5
	s_sext_i32_i8 s4, s4
	s_lshl_b32 s4, s4, 7
	s_ashr_i32 s5, s4, 31
	s_add_i32 s24, s3, 31
	s_lshl_b64 s[4:5], s[4:5], 1
	s_add_u32 s6, s10, s4
	s_addc_u32 s7, s11, s5
	s_add_u32 s28, s12, s4
	s_addc_u32 s29, s13, s5
	s_add_u32 s34, s18, s4
	s_getreg_b32 s8, hwreg(HW_REG_HW_ID, 0, 6)
	s_addc_u32 s35, s19, s5
	s_lshl_b32 s8, s8, 2
	s_and_b32 s8, s8, 0xfc
	s_add_i32 s8, s8, 0x20040
	v_mov_b32_e32 v0, s8
	ds_read_b32 v0, v0
	s_lshl_b32 s25, s24, 7
	v_mov_b64_e32 v[8:9], s[28:29]
	v_mov_b64_e32 v[12:13], s[34:35]
	s_lshl_b32 s24, s24, 1
	s_waitcnt lgkmcnt(0)
	v_readfirstlane_b32 s8, v0
	v_mov_b32_e32 v0, v1
	v_mov_b32_e32 v3, v1
	v_mbcnt_lo_u32_b32 v0, -1, v0
	v_mbcnt_hi_u32_b32 v6, -1, v0
	v_lshl_or_b32 v0, s8, 6, v6
	s_bfe_i64 s[8:9], s[2:3], 0x100000
	v_readfirstlane_b32 s23, v0
	s_ashr_i32 s26, s23, 6
	s_ashr_i32 s23, s23, 7
	s_lshl_b32 s27, s23, 5
	s_add_i32 s27, s27, s25
	s_lshl_b32 s25, s26, 3
	v_bfe_u32 v16, v6, 4, 2
	s_lshl_b64 s[8:9], s[8:9], 12
	v_or_b32_e32 v0, s25, v16
	v_lshl_add_u64 v[4:5], s[8:9], 0, v[0:1]
	s_lshl_b32 s44, s26, 1
	v_mad_u64_u32 v[10:11], s[28:29], v4, s84, v[8:9]
	v_mad_u64_u32 v[14:15], s[28:29], v4, s84, v[12:13]
	s_or_b32 s25, s25, 4
	v_and_b32_e32 v17, 15, v6
	v_lshlrev_b32_e32 v18, 2, v16
	s_and_b32 s44, s44, 2
	v_mad_i32_i24 v11, v5, s84, v11
	v_mad_i32_i24 v15, v5, s84, v15
	v_or_b32_e32 v4, s25, v16
	s_bfe_u32 s25, s25, 0x20002
	v_mov_b32_e32 v5, v1
	s_ashr_i32 s33, s27, 31
	v_bitop3_b32 v2, s44, v17, v18 bitop3:0x36
	v_bitop3_b32 v18, s25, v17, v18 bitop3:0x36
	v_lshl_add_u64 v[16:17], s[8:9], 0, v[4:5]
	s_ashr_i32 s25, s27, 6
	v_mad_u64_u32 v[8:9], s[28:29], v16, s84, v[8:9]
	v_mad_u64_u32 v[12:13], s[28:29], v16, s84, v[12:13]
	s_add_u32 s27, s8, s27
	s_addc_u32 s28, s9, s33
	s_lshl_b32 s9, s26, 11
	v_lshlrev_b32_e32 v2, 4, v2
	s_add_i32 s9, s9, 0
	v_lshl_add_u64 v[10:11], v[10:11], 0, v[2:3]
	v_mad_i32_i24 v9, v17, s84, v9
	v_lshlrev_b32_e32 v4, 4, v18
	s_mov_b32 m0, s9
	v_lshl_add_u64 v[8:9], v[8:9], 0, v[4:5]
	global_load_lds_dwordx4 v[10:11], off
	s_add_i32 m0, s9, 0x400
	v_lshl_add_u64 v[14:15], v[14:15], 0, v[2:3]
	v_mad_i32_i24 v13, v17, s84, v13
	global_load_lds_dwordx4 v[8:9], off
	s_add_i32 m0, s9, 0x4000
	v_lshl_add_u64 v[12:13], v[12:13], 0, v[4:5]
	global_load_lds_dwordx4 v[14:15], off
	s_add_i32 m0, s9, 0x4400
	v_lshl_add_u64 v[10:11], v[10:11], 0, s[60:61]
	global_load_lds_dwordx4 v[12:13], off
	s_add_i32 m0, s9, 0xa000
	v_lshl_add_u64 v[8:9], v[8:9], 0, s[60:61]
	global_load_lds_dwordx4 v[10:11], off
	s_add_i32 m0, s9, 0xa400
	v_and_b32_e32 v7, 31, v6
	global_load_lds_dwordx4 v[8:9], off
	v_lshl_add_u64 v[8:9], v[14:15], 0, s[60:61]
	s_add_i32 m0, s9, 0xe000
	v_or_b32_e32 v114, s27, v7
	global_load_lds_dwordx4 v[8:9], off
	v_lshl_add_u64 v[8:9], v[12:13], 0, s[60:61]
	s_add_i32 m0, s9, 0xe400
	s_and_b32 s8, s26, 1
	global_load_lds_dwordx4 v[8:9], off
	v_mov_b64_e32 v[8:9], s[6:7]
	v_mad_u64_u32 v[8:9], s[6:7], v114, s84, v[8:9]
	v_mov_b32_e32 v10, 0xa00
	v_bfe_u32 v16, v6, 5, 1
	v_mad_i32_i24 v9, s28, v10, v9
	s_lshl_b32 s68, s8, 7
	v_lshl_add_u64 v[8:9], v[8:9], 0, s[68:69]
	v_lshlrev_b32_e32 v10, 4, v16
	v_mov_b32_e32 v11, v1
	v_lshl_add_u64 v[8:9], v[8:9], 0, v[10:11]
	global_load_dwordx4 v[98:101], v[8:9], off
	global_load_dwordx4 v[102:105], v[8:9], off offset:32
	global_load_dwordx4 v[106:109], v[8:9], off offset:64
	global_load_dwordx4 v[110:113], v[8:9], off offset:96
	v_lshlrev_b32_e32 v17, 2, v6
	v_bfe_u32 v18, v6, 2, 2
	v_and_or_b32 v8, v17, 12, v18
	s_lshl_b32 s6, s8, 3
	v_lshlrev_b32_e32 v9, 3, v6
	v_mov_b32_e32 v10, 0x4000
	v_lshrrev_b32_e32 v19, 3, v6
	v_lshlrev_b32_e32 v124, 8, v7
	v_or_b32_e32 v7, s6, v16
	v_and_or_b32 v125, v9, 8, v10
	v_bitop3_b32 v9, s6, v8, v16 bitop3:0x36
	v_and_b32_e32 v19, 2, v19
	v_bfe_u32 v20, v6, 1, 1
	v_lshlrev_b32_e32 v126, 4, v9
	v_bitop3_b32 v9, v7, v8, 2 bitop3:0x36
	v_or_b32_e32 v21, v19, v20
	v_lshlrev_b32_e32 v127, 4, v9
	v_bitop3_b32 v9, v7, v8, 4 bitop3:0x36
	v_bitop3_b32 v7, v7, v8, 6 bitop3:0x36
	v_bitop3_b32 v19, v19, v16, v20 bitop3:0x36
	v_bitop3_b32 v23, v16, v21, 2 bitop3:0x36
	v_lshlrev_b32_e32 v129, 4, v7
	v_and_b32_e32 v7, 12, v6
	v_or_b32_e32 v8, v19, v7
	v_or_b32_e32 v7, v23, v7
	v_or_b32_e32 v20, 2, v16
	v_lshlrev_b32_e32 v133, 4, v7
	v_bitop3_b32 v7, v6, 4, 12 bitop3:0x6c
	v_lshlrev_b32_e32 v131, 4, v8
	v_bitop3_b32 v8, v21, v7, v16 bitop3:0xde
	v_bitop3_b32 v7, v20, v7, v21 bitop3:0xde
	v_lshlrev_b32_e32 v141, 4, v7
	v_bitop3_b32 v7, v6, 8, 12 bitop3:0x6c
	v_and_b32_e32 v123, 63, v6
	v_lshlrev_b32_e32 v140, 4, v8
	v_bitop3_b32 v8, v21, v7, v16 bitop3:0xde
	v_bitop3_b32 v7, v20, v7, v21 bitop3:0xde
	v_bitop3_b32 v6, v6, 12, v6 bitop3:0xc
	v_lshlrev_b32_e32 v143, 4, v7
	v_bitop3_b32 v7, v21, v6, v16 bitop3:0xde
	v_bitop3_b32 v6, v20, v6, v21 bitop3:0xde
	v_lshlrev_b32_e32 v145, 4, v6
	v_or_b32_e32 v6, 4, v0
	v_lshlrev_b32_e32 v144, 4, v7
	v_mad_u64_u32 v[6:7], s[6:7], v6, s84, 0
	s_sext_i32_i16 s2, s2
	v_mad_i64_i32 v[6:7], s[6:7], s2, v214, v[6:7]
	v_lshl_add_u64 v[4:5], v[6:7], 0, v[4:5]
	v_lshl_add_u64 v[116:117], s[14:15], 0, v[4:5]
	v_mad_u64_u32 v[4:5], s[6:7], v0, s84, 0
	v_lshlrev_b32_e32 v122, 2, v16
	v_mad_i64_i32 v[4:5], s[6:7], s2, v214, v[4:5]
	v_or_b32_e32 v22, v122, v18
	v_lshl_add_u64 v[2:3], v[4:5], 0, v[2:3]
	v_mov_b32_e32 v14, v1
	v_mov_b32_e32 v15, v1
	s_waitcnt vmcnt(0)
	s_waitcnt vmcnt(0) lgkmcnt(0)
	s_barrier
; template <int MODE>
; __device__ __forceinline__ void attn_unit(LAS char* lds, const AttnPtrs& A, int b, int qb) {
;     ...
;     f32x16 o1[4];
; #pragma unroll
;     for (int c = 0; c < 4; ++c) o1[c] = f32x16{};
;     float m1 = -1e30f, l1 = 0.f;
;     unsigned long long mw_next = 0ull;
;     if constexpr (MODE == 1) { mw_next = A.MASK[qrow * 64]; asm volatile("" : "+v"(mw_next)); }
;     bf16x8 pk[4]; float a1 = 1.f;
;     ...
;     int st_cur = 0, st_nn = 2;
	v_lshlrev_b32_e32 v128, 4, v9
	v_lshlrev_b32_e32 v130, 8, v22
	v_lshlrev_b32_e32 v142, 4, v8
	v_lshl_add_u64 v[118:119], s[14:15], 0, v[2:3]
	v_mov_b32_e32 v0, v1
	v_mov_b32_e32 v2, v1
	v_mov_b32_e32 v3, v1
	v_mov_b32_e32 v4, v1
	v_mov_b32_e32 v5, v1
	v_mov_b32_e32 v6, v1
	v_mov_b32_e32 v7, v1
	v_mov_b32_e32 v8, v1
	v_mov_b32_e32 v9, v1
	v_mov_b32_e32 v10, v1
	v_mov_b32_e32 v12, v1
	v_mov_b32_e32 v13, v1
	v_mov_b64_e32 v[64:65], v[14:15]
	v_mov_b64_e32 v[48:49], v[14:15]
	v_mov_b64_e32 v[32:33], v[14:15]
	s_lshl_b32 s6, s3, 1
	v_mov_b64_e32 v[62:63], v[12:13]
	v_mov_b64_e32 v[60:61], v[10:11]
	v_mov_b64_e32 v[58:59], v[8:9]
	v_mov_b64_e32 v[56:57], v[6:7]
	v_mov_b64_e32 v[54:55], v[4:5]
	v_mov_b64_e32 v[52:53], v[2:3]
	v_mov_b64_e32 v[50:51], v[0:1]
	v_mov_b64_e32 v[46:47], v[12:13]
	v_mov_b64_e32 v[44:45], v[10:11]
	v_mov_b64_e32 v[42:43], v[8:9]
	v_mov_b64_e32 v[40:41], v[6:7]
	v_mov_b64_e32 v[38:39], v[4:5]
	v_mov_b64_e32 v[36:37], v[2:3]
	v_mov_b64_e32 v[34:35], v[0:1]
	v_mov_b64_e32 v[30:31], v[12:13]
	v_mov_b64_e32 v[28:29], v[10:11]
	v_mov_b64_e32 v[26:27], v[8:9]
	v_mov_b64_e32 v[24:25], v[6:7]
	v_mov_b64_e32 v[22:23], v[4:5]
	v_mov_b64_e32 v[20:21], v[2:3]
	v_mov_b64_e32 v[18:19], v[0:1]
	v_mov_b64_e32 v[16:17], v[14:15]
	s_mov_b32 s16, 2
	s_mov_b32 s17, 0
	v_mov_b32_e32 v115, s28
	v_or_b32_e32 v132, 0x800, v130
	v_or_b32_e32 v134, 0x1000, v130
	v_or_b32_e32 v135, 0x1800, v130
	v_or_b32_e32 v136, 0x2000, v130
	v_or_b32_e32 v137, 0x2800, v130
	v_or_b32_e32 v138, 0x3000, v130
	v_or_b32_e32 v139, 0x3800, v130
	s_add_i32 s6, s6, 64
	v_mov_b32_e32 v148, 0xf149f2ca
	v_mov_b32_e32 v252, 0
	v_mov_b64_e32 v[236:237], 0
	v_mov_b64_e32 v[238:239], 0
	v_mov_b64_e32 v[240:241], 0
	v_mov_b64_e32 v[242:243], 0
	v_mov_b64_e32 v[244:245], 0
	v_mov_b64_e32 v[246:247], 0
	v_mov_b64_e32 v[248:249], 0
	v_mov_b64_e32 v[250:251], 0
	v_mov_b32_e32 v147, 0
	v_mov_b64_e32 v[14:15], v[12:13]
	v_mov_b64_e32 v[12:13], v[10:11]
	v_mov_b64_e32 v[10:11], v[8:9]
	v_mov_b64_e32 v[8:9], v[6:7]
	v_mov_b64_e32 v[6:7], v[4:5]
	v_mov_b64_e32 v[4:5], v[2:3]
	v_mov_b64_e32 v[2:3], v[0:1]
	s_mov_b32 s7, 0
	s_cmp_ge_u32 s7, s24
	s_cselect_b64 s[2:3], -1, 0
	s_and_b64 vcc, exec, s[2:3]
	s_cbranch_vccnz .LBB0_626
	s_branch .LBB0_625

; __device__ __forceinline__ float max_x32(float v) { const unsigned u = __float_as_uint(v); auto r = __builtin_amdgcn_permlane32_swap(u, u, false, false); return fmaxf(__uint_as_float(r[0]), __uint_as_float(r[1])); }
; template <bool MASKED>
; __device__ __forceinline__ void softmax_tile(f32x16& s0, f32x16& s1, float& m, float& l, float& alpha, unsigned mlo, unsigned mhi, bf16x8 (&pk)[4]) {
;     ...
;     float mx = fmaxf(s0[0], s1[0]);
; #pragma unroll
;     for (int r = 1; r < 16; ++r) mx = fmaxf(mx, fmaxf(s0[r], s1[r]));
;     mx = max_x32(mx);
;     const float mn = fmaxf(m, mx);
;     alpha = __builtin_amdgcn_exp2f(m - mn); m = mn;
.LBB0_626:
	s_cmp_gt_i32 s7, s25
	s_cbranch_scc1 .LBB0_630
	s_mul_i32 s26, s17, 0xa000
	s_add_i32 s26, s26, 0
	v_add_u32_e32 v0, s26, v124
	v_add_u32_e32 v70, v0, v126
	v_add_u32_e32 v74, v0, v127
	ds_read_b128 v[66:69], v70
	ds_read_b128 v[70:73], v70 offset:8192
	ds_read_b128 v[150:153], v74
	ds_read_b128 v[154:157], v74 offset:8192
	v_add_u32_e32 v74, v0, v128
	v_add_u32_e32 v0, v0, v129
	ds_read_b128 v[158:161], v74
	ds_read_b128 v[162:165], v74 offset:8192
	ds_read_b128 v[166:169], v0
	ds_read_b128 v[170:173], v0 offset:8192
	s_waitcnt lgkmcnt(0)
	v_mfma_f32_32x32x16_bf16 v[82:97], v[66:69], v[98:101], v[236:251]
	v_mfma_f32_32x32x16_bf16 v[66:81], v[70:73], v[98:101], v[236:251]
	v_mfma_f32_32x32x16_bf16 v[82:97], v[150:153], v[102:105], v[82:97]
	v_mfma_f32_32x32x16_bf16 v[66:81], v[154:157], v[102:105], v[66:81]
	v_mfma_f32_32x32x16_bf16 v[82:97], v[158:161], v[106:109], v[82:97]
	v_mfma_f32_32x32x16_bf16 v[66:81], v[162:165], v[106:109], v[66:81]
	v_mfma_f32_32x32x16_bf16 v[82:97], v[166:169], v[110:113], v[82:97]
	v_mfma_f32_32x32x16_bf16 v[66:81], v[170:173], v[110:113], v[66:81]
	s_nop 11
	v_max3_f32 v150, v82, v83, v84
	v_max3_f32 v151, v85, v86, v87
	v_max3_f32 v152, v88, v89, v90
	v_max3_f32 v153, v91, v92, v93
	v_max3_f32 v154, v94, v95, v96
	v_max3_f32 v155, v97, v66, v67
	v_max3_f32 v156, v68, v69, v70
	v_max3_f32 v157, v71, v72, v73
	v_max3_f32 v158, v74, v75, v76
	v_max3_f32 v159, v77, v78, v79
	v_max3_f32 v150, v150, v151, v152
	v_max3_f32 v153, v153, v154, v155
	v_max3_f32 v156, v156, v157, v158
	v_max3_f32 v159, v159, v80, v81
	v_max3_f32 v150, v150, v153, v156
	v_max_f32_e32 v150, v150, v159
	v_mov_b32_e32 v151, v150
	s_nop 1
	v_permlane32_swap_b32_e32 v150, v151
	v_max_f32_e32 v146, v150, v151
	v_add_f32_e32 v146, v146, v252
	v_max_f32_e32 v146, v148, v146
	v_sub_f32_e32 v150, v146, v148
	v_cmp_lt_f32_e32 vcc, 8.0, v150
	s_nop 1
	v_cndmask_b32_e32 v146, v148, v146, vcc
	v_sub_f32_e32 v0, v148, v146
	v_sub_f32_e32 v150, v146, v252
	v_cmp_neq_f32_e32 vcc, 0, v150
	s_cbranch_vccz .Lm2_cfast
	v_sub_f32_e32 v82, v82, v150
	v_sub_f32_e32 v83, v83, v150
	v_sub_f32_e32 v84, v84, v150
	v_sub_f32_e32 v85, v85, v150
	v_sub_f32_e32 v86, v86, v150
	v_sub_f32_e32 v87, v87, v150
	v_sub_f32_e32 v88, v88, v150
	v_sub_f32_e32 v89, v89, v150
	v_sub_f32_e32 v90, v90, v150
	v_sub_f32_e32 v91, v91, v150
	v_sub_f32_e32 v92, v92, v150
	v_sub_f32_e32 v93, v93, v150
	v_sub_f32_e32 v94, v94, v150
	v_sub_f32_e32 v95, v95, v150
	v_sub_f32_e32 v96, v96, v150
	v_sub_f32_e32 v97, v97, v150
	v_sub_f32_e32 v66, v66, v150
	v_sub_f32_e32 v67, v67, v150
	v_sub_f32_e32 v68, v68, v150
	v_sub_f32_e32 v69, v69, v150
	v_sub_f32_e32 v70, v70, v150
	v_sub_f32_e32 v71, v71, v150
	v_sub_f32_e32 v72, v72, v150
	v_sub_f32_e32 v73, v73, v150
	v_sub_f32_e32 v74, v74, v150
	v_sub_f32_e32 v75, v75, v150
	v_sub_f32_e32 v76, v76, v150
	v_sub_f32_e32 v77, v77, v150
	v_sub_f32_e32 v78, v78, v150
	v_sub_f32_e32 v79, v79, v150
	v_sub_f32_e32 v80, v80, v150
	v_sub_f32_e32 v81, v81, v150
	v_mov_b32_e32 v252, v146
	v_sub_f32_e32 v236, 0, v146
	v_sub_f32_e32 v237, 0, v146
	v_sub_f32_e32 v238, 0, v146
	v_sub_f32_e32 v239, 0, v146
	v_sub_f32_e32 v240, 0, v146
	v_sub_f32_e32 v241, 0, v146
	v_sub_f32_e32 v242, 0, v146
	v_sub_f32_e32 v243, 0, v146
	v_sub_f32_e32 v244, 0, v146
	v_sub_f32_e32 v245, 0, v146
	v_sub_f32_e32 v246, 0, v146
	v_sub_f32_e32 v247, 0, v146
	v_sub_f32_e32 v248, 0, v146
	v_sub_f32_e32 v249, 0, v146
	v_sub_f32_e32 v250, 0, v146
	v_sub_f32_e32 v251, 0, v146
; __device__ __forceinline__ unsigned cvtpk(float lo, float hi) { unsigned r; asm("v_cvt_pk_bf16_f32 %0, %1, %2" : "=v"(r) : "v"(lo), "v"(hi)); return r; }
; template <bool MASKED>
; __device__ __forceinline__ void softmax_tile(f32x16& s0, f32x16& s1, float& m, float& l, float& alpha, unsigned mlo, unsigned mhi, bf16x8 (&pk)[4]) {
;     ...
;     alpha = __builtin_amdgcn_exp2f(m - mn); m = mn;
;     float sum = 0.f;
; #pragma unroll
;     for (int r = 0; r < 16; ++r) {
;         float p0 = __builtin_amdgcn_exp2f(s0[r] - mn), p1 = __builtin_amdgcn_exp2f(s1[r] - mn);
;         if (MASKED) { if (s0[r] <= -1e29f) p0 = 0.f; if (s1[r] <= -1e29f) p1 = 0.f; }
;         s0[r] = p0; s1[r] = p1; sum += p0 + p1;
;     }
;     l = l * alpha + sum;
; #pragma unroll
;     for (int k2 = 0; k2 < 2; ++k2) {
;         u32x4 a, b;
;         a.x = cvtpk(s0[8 * k2 + 0], s0[8 * k2 + 1]); a.y = cvtpk(s0[8 * k2 + 2], s0[8 * k2 + 3]); a.z = cvtpk(s0[8 * k2 + 4], s0[8 * k2 + 5]); a.w = cvtpk(s0[8 * k2 + 6], s0[8 * k2 + 7]);
;         b.x = cvtpk(s1[8 * k2 + 0], s1[8 * k2 + 1]); b.y = cvtpk(s1[8 * k2 + 2], s1[8 * k2 + 3]); b.z = cvtpk(s1[8 * k2 + 4], s1[8 * k2 + 5]); b.w = cvtpk(s1[8 * k2 + 6], s1[8 * k2 + 7]);
;         pk[k2] = __builtin_bit_cast(bf16x8, a); pk[2 + k2] = __builtin_bit_cast(bf16x8, b);
;     }
.Lm2_cfast:
	v_exp_f32_e32 v0, v0
	v_exp_f32_e32 v82, v82
	v_exp_f32_e32 v83, v83
	v_exp_f32_e32 v84, v84
	v_exp_f32_e32 v85, v85
	v_exp_f32_e32 v86, v86
	v_exp_f32_e32 v87, v87
	v_exp_f32_e32 v88, v88
	v_exp_f32_e32 v89, v89
	v_exp_f32_e32 v90, v90
	v_exp_f32_e32 v91, v91
	v_exp_f32_e32 v92, v92
	v_exp_f32_e32 v93, v93
	v_exp_f32_e32 v94, v94
	v_exp_f32_e32 v95, v95
	v_exp_f32_e32 v96, v96
	v_exp_f32_e32 v97, v97
	v_exp_f32_e32 v66, v66
	v_exp_f32_e32 v67, v67
	v_exp_f32_e32 v68, v68
	v_exp_f32_e32 v69, v69
	v_exp_f32_e32 v70, v70
	v_exp_f32_e32 v71, v71
	v_exp_f32_e32 v72, v72
	v_exp_f32_e32 v73, v73
	v_exp_f32_e32 v74, v74
	v_exp_f32_e32 v75, v75
	v_exp_f32_e32 v76, v76
	v_exp_f32_e32 v77, v77
	v_exp_f32_e32 v78, v78
	v_exp_f32_e32 v79, v79
	v_exp_f32_e32 v80, v80
	v_exp_f32_e32 v81, v81
	v_pk_add_f32 v[150:151], v[82:83], v[84:85]
	v_pk_add_f32 v[152:153], v[86:87], v[88:89]
	v_pk_add_f32 v[154:155], v[90:91], v[92:93]
	v_pk_add_f32 v[156:157], v[94:95], v[96:97]
	v_pk_add_f32 v[158:159], v[66:67], v[68:69]
	v_pk_add_f32 v[160:161], v[70:71], v[72:73]
	v_pk_add_f32 v[162:163], v[74:75], v[76:77]
	v_pk_add_f32 v[164:165], v[78:79], v[80:81]
	v_pk_add_f32 v[150:151], v[150:151], v[152:153]
	v_pk_add_f32 v[154:155], v[154:155], v[156:157]
	v_pk_add_f32 v[158:159], v[158:159], v[160:161]
	v_pk_add_f32 v[162:163], v[162:163], v[164:165]
	v_pk_add_f32 v[150:151], v[150:151], v[154:155]
	v_pk_add_f32 v[158:159], v[158:159], v[162:163]
	v_pk_add_f32 v[150:151], v[150:151], v[158:159]
	v_add_f32_e32 v164, v150, v151
	v_cvt_pk_bf16_f32 v66, v66, v67
	v_cvt_pk_bf16_f32 v67, v68, v69
	v_cvt_pk_bf16_f32 v68, v70, v71
	v_cvt_pk_bf16_f32 v69, v72, v73
	v_cvt_pk_bf16_f32 v70, v74, v75
	v_cvt_pk_bf16_f32 v71, v76, v77
	v_cvt_pk_bf16_f32 v72, v78, v79
	v_cvt_pk_bf16_f32 v73, v80, v81
	v_cvt_pk_bf16_f32 v74, v82, v83
	v_cvt_pk_bf16_f32 v75, v84, v85
	v_cvt_pk_bf16_f32 v76, v86, v87
	v_cvt_pk_bf16_f32 v77, v88, v89
	v_cvt_pk_bf16_f32 v78, v90, v91
	v_cvt_pk_bf16_f32 v79, v92, v93
	v_cvt_pk_bf16_f32 v80, v94, v95
	v_cvt_pk_bf16_f32 v81, v96, v97
	v_fmac_f32_e32 v164, v147, v0
	v_cmp_neq_f32_e32 vcc, 1.0, v0
	s_cbranch_vccz .LBB0_629
	v_pk_mul_f32 v[64:65], v[64:65], v[0:1] op_sel_hi:[1,0]
	v_pk_mul_f32 v[62:63], v[62:63], v[0:1] op_sel_hi:[1,0]
	v_pk_mul_f32 v[60:61], v[60:61], v[0:1] op_sel_hi:[1,0]
	v_pk_mul_f32 v[58:59], v[58:59], v[0:1] op_sel_hi:[1,0]
	v_pk_mul_f32 v[56:57], v[56:57], v[0:1] op_sel_hi:[1,0]
	v_pk_mul_f32 v[54:55], v[54:55], v[0:1] op_sel_hi:[1,0]
	v_pk_mul_f32 v[52:53], v[52:53], v[0:1] op_sel_hi:[1,0]
	v_pk_mul_f32 v[50:51], v[50:51], v[0:1] op_sel_hi:[1,0]
	v_pk_mul_f32 v[48:49], v[48:49], v[0:1] op_sel_hi:[1,0]
	v_pk_mul_f32 v[46:47], v[46:47], v[0:1] op_sel_hi:[1,0]
	v_pk_mul_f32 v[44:45], v[44:45], v[0:1] op_sel_hi:[1,0]
	v_pk_mul_f32 v[42:43], v[42:43], v[0:1] op_sel_hi:[1,0]
	v_pk_mul_f32 v[40:41], v[40:41], v[0:1] op_sel_hi:[1,0]
	v_pk_mul_f32 v[38:39], v[38:39], v[0:1] op_sel_hi:[1,0]
	v_pk_mul_f32 v[36:37], v[36:37], v[0:1] op_sel_hi:[1,0]
	v_pk_mul_f32 v[34:35], v[34:35], v[0:1] op_sel_hi:[1,0]
	v_pk_mul_f32 v[32:33], v[32:33], v[0:1] op_sel_hi:[1,0]
	v_pk_mul_f32 v[30:31], v[30:31], v[0:1] op_sel_hi:[1,0]
	v_pk_mul_f32 v[28:29], v[28:29], v[0:1] op_sel_hi:[1,0]
	v_pk_mul_f32 v[26:27], v[26:27], v[0:1] op_sel_hi:[1,0]
	v_pk_mul_f32 v[24:25], v[24:25], v[0:1] op_sel_hi:[1,0]
	v_pk_mul_f32 v[22:23], v[22:23], v[0:1] op_sel_hi:[1,0]
	v_pk_mul_f32 v[20:21], v[20:21], v[0:1] op_sel_hi:[1,0]
	v_pk_mul_f32 v[18:19], v[18:19], v[0:1] op_sel_hi:[1,0]
	v_pk_mul_f32 v[16:17], v[16:17], v[0:1] op_sel_hi:[1,0]
	v_pk_mul_f32 v[14:15], v[14:15], v[0:1] op_sel_hi:[1,0]
	v_pk_mul_f32 v[12:13], v[12:13], v[0:1] op_sel_hi:[1,0]
	v_pk_mul_f32 v[10:11], v[10:11], v[0:1] op_sel_hi:[1,0]
	v_pk_mul_f32 v[8:9], v[8:9], v[0:1] op_sel_hi:[1,0]
	v_pk_mul_f32 v[6:7], v[6:7], v[0:1] op_sel_hi:[1,0]
	v_pk_mul_f32 v[4:5], v[4:5], v[0:1] op_sel_hi:[1,0]
	v_pk_mul_f32 v[2:3], v[2:3], v[0:1] op_sel_hi:[1,0]
